# attention: keep next-tile K/V prefetch in flight (drop vmcnt drain at QK MFMA), permute V^T key order so V fragments load with ds_read_b128 instead of ds_read2_b64
# speedup vs baseline: 1.0192x; 1.0192x over previous
; __device__ __forceinline__ void phase_attn_prep(KP P, int l_, unsigned char* shm) {
;     ...
;         for (int it = blockIdx.x; it < 4096; it += gridDim.x) {
;             const int bh = it >> 5, sb = it & 31, b = bh >> 2, h = bh & 3;
;             const u16* src = pA + ((size_t)b * SEQ + sb * 64 + ts) * 1536 + 1024 + h * 128 + tc * 16;
;             const uint4 a0 = *(const uint4*)src, a1 = *(const uint4*)(src + 8);
;             *(uint4*)(tile + ts * 136 + tc * 16) = a0; *(uint4*)(tile + ts * 136 + tc * 16 + 8) = a1;
;             __syncthreads();
;             unsigned w[8];
; #pragma unroll
;             for (int j = 0; j < 8; ++j) w[j] = (unsigned)tile[(tq * 16 + 2 * j) * 136 + te] | ((unsigned)tile[(tq * 16 + 2 * j + 1) * 136 + te] << 16);
;             u16* dst = vT + ((size_t)bh * 128 + te) * SEQ + sb * 64 + tq * 16;
;             uint4 o0, o1; o0.x = w[0]; o0.y = w[1]; o0.z = w[2]; o0.w = w[3]; o1.x = w[4]; o1.y = w[5]; o1.z = w[6]; o1.w = w[7];
;             *(uint4*)dst = o0; *(uint4*)(dst + 8) = o1;
;             __syncthreads();
;         }
.LBB0_2591:
	s_or_b64 exec, exec, s[8:9]
	v_readlane_b32 s0, v254, 6
	v_readlane_b32 s1, v254, 7
	s_andn2_b64 vcc, exec, s[0:1]
	s_cbranch_vccnz .LBB0_2594
	v_lshlrev_b32_e32 v3, 4, v58
	v_ashrrev_i32_e32 v0, 3, v58
	v_and_b32_e32 v4, 0x70, v3
	s_movk_i32 s0, 0x110
	v_ashrrev_i32_e32 v2, 2, v58
	v_mul_lo_u32 v6, v0, s0
	v_lshlrev_b32_e32 v7, 1, v4
	v_add3_u32 v8, 0, v6, v7
	v_and_b32_e32 v6, 48, v3
	v_ashrrev_i32_e32 v3, 31, v2
	v_lshlrev_b32_e32 v7, 1, v2
	v_lshlrev_b64 v[2:3], 12, v[2:3]
	v_and_b32_e32 v11, 2, v58
	v_and_b32_e32 v12, 1, v58
	v_lshlrev_b32_e32 v11, 4, v11
	v_lshl_or_b32 v11, v12, 3, v11
	v_mul_u32_u24_e32 v9, 0x88, v11
	v_lshl_add_u64 v[2:3], s[6:7], 0, v[2:3]
	s_mov_b64 s[0:1], 0x2bb00000
	v_lshlrev_b32_e32 v10, 1, v9
	v_ashrrev_i32_e32 v1, 31, v0
	v_lshl_add_u64 v[2:3], v[2:3], 0, s[0:1]
	v_add3_u32 v9, 0, v7, v10
	v_add3_u32 v10, 0, v10, v7
	v_lshlrev_b32_e32 v4, 1, v4
	v_lshlrev_b32_e32 v6, 1, v6
	v_readlane_b32 s8, v254, 25
	s_mov_b32 s9, s2
.LBB0_2593:
	s_ashr_i32 s10, s9, 7
	s_ashr_i32 s11, s10, 31
	s_lshl_b64 s[10:11], s[10:11], 11
	s_and_b32 s0, s8, 0x7c0
	s_or_b32 s10, s10, s0
	s_ashr_i32 s6, s9, 5
	v_lshl_add_u64 v[12:13], s[10:11], 0, v[0:1]
	v_mov_b64_e32 v[14:15], s[4:5]
	v_mad_u64_u32 v[14:15], s[10:11], v12, s83, v[14:15]
	s_lshl_b32 s1, s6, 8
	v_mad_i32_i24 v15, v13, s83, v15
	s_and_b32 s52, s1, 0x300
	v_lshl_add_u64 v[12:13], v[14:15], 0, s[52:53]
	v_lshl_add_u64 v[16:17], v[12:13], 0, v[4:5]
	global_load_dwordx4 v[12:15], v[16:17], off offset:2064
	s_nop 0
	global_load_dwordx4 v[16:19], v[16:17], off offset:2048
	s_ashr_i32 s7, s6, 31
	s_lshl_b64 s[6:7], s[6:7], 19
	v_lshl_add_u64 v[20:21], v[2:3], 0, s[6:7]
	s_lshl_b32 s52, s0, 1
	v_lshl_add_u64 v[20:21], v[20:21], 0, s[52:53]
	s_add_i32 s9, s9, s44
	s_add_i32 s8, s8, s78
	s_cmpk_gt_i32 s9, 0xfff
	s_waitcnt vmcnt(0)
	ds_write_b128 v8, v[16:19]
	ds_write_b128 v8, v[12:15] offset:16
	s_waitcnt lgkmcnt(0)
	s_barrier
	ds_read_u16 v7, v9
	ds_read_u16 v11, v10 offset:272
	s_waitcnt lgkmcnt(0)
	v_lshl_or_b32 v12, v11, 16, v7
	ds_read_u16 v7, v9 offset:544
	ds_read_u16 v11, v10 offset:816
	s_waitcnt lgkmcnt(0)
	v_lshl_or_b32 v13, v11, 16, v7
	ds_read_u16 v7, v9 offset:4352
	ds_read_u16 v11, v10 offset:4624
	s_waitcnt lgkmcnt(0)
	v_lshl_or_b32 v14, v11, 16, v7
	ds_read_u16 v7, v9 offset:4896
	ds_read_u16 v11, v10 offset:5168
	s_waitcnt lgkmcnt(0)
	v_lshl_or_b32 v15, v11, 16, v7
	ds_read_u16 v7, v9 offset:1088
	ds_read_u16 v11, v10 offset:1360
	s_waitcnt lgkmcnt(0)
	v_lshl_or_b32 v16, v11, 16, v7
	ds_read_u16 v7, v9 offset:1632
	ds_read_u16 v11, v10 offset:1904
	s_waitcnt lgkmcnt(0)
	v_lshl_or_b32 v17, v11, 16, v7
	ds_read_u16 v7, v9 offset:5440
	ds_read_u16 v11, v10 offset:5712
	s_waitcnt lgkmcnt(0)
	v_lshl_or_b32 v18, v11, 16, v7
	ds_read_u16 v7, v9 offset:5984
	ds_read_u16 v11, v10 offset:6256
	s_waitcnt lgkmcnt(0)
	v_lshl_or_b32 v19, v11, 16, v7
	v_mov_b32_e32 v7, v5
	v_lshl_add_u64 v[20:21], v[20:21], 0, v[6:7]
	global_store_dwordx4 v[20:21], v[12:15], off
	global_store_dwordx4 v[20:21], v[16:19], off offset:16
	s_barrier
	s_cbranch_scc0 .LBB0_2593

; __device__ __forceinline__ void phase_attn(KP P, int l_, unsigned char* shm) {
;     ...
;         const int j = it & 255, pi = 15 - (it >> 8), bh = j >> 1, half = j & 1, b = bh >> 2, h = bh & 3;
;         const int qb = (pi >> 1) * 4 + ((pi & 1) ? (half ? 2 : 3) : (half ? 1 : 0));
;         const int q0 = qb * 64, nt = (qb >> 1) + 1;
;         const size_t tok0 = (size_t)b * SEQ;
;         bf16x8 qf[2];
;         { const u16* qp = pA + (tok0 + q0 + rq * 16 + l15) * 1536 + h * 128 + mp * 64 + g * 8;
;           qf[0] = *(const bf16x8*)qp; qf[1] = *(const bf16x8*)(qp + 32); }
;         f32x4 ot[8];
; #pragma unroll
;         for (int e = 0; e < 8; ++e) ot[e] = (f32x4){0.f, 0.f, 0.f, 0.f};
;         float mrun = -INFINITY, lrun = 0.f;
;         uint4 kreg0, kreg1, kreg2, kreg3, vreg0, vreg1, vreg2, vreg3;
;         const int kc_key = (tid >> 3) & 63, kc_ch = tid & 7, vc_e = tid >> 4, vc_ch = tid & 15;
;         const u16* kgb = pA + (tok0 + kc_key) * 1536 + 512 + h * 128 + kc_ch * 8;
;         const u16* vTb = vTg + ((size_t)bh * 128 + vc_e) * SEQ + vc_ch * 8;
;     ...
;         ATT_GLOAD(0); ATT_LSTORE(0); __syncthreads();
.LBB0_2649:
	s_bfe_u32 s0, s62, 0x70001
	s_lshl_b32 s52, s0, 19
	v_lshl_add_u64 v[174:175], v[166:167], 0, s[52:53]
	s_ashr_i32 s52, s62, 8
	s_sub_i32 s52, 15, s52
	s_lshl_b32 s1, s62, 7
	s_and_b32 s56, s62, 1
	s_lshl_b32 s57, s52, 1
	s_and_b32 s1, s1, 0x300
	s_and_b32 s57, s57, 0x7ffffffc
	s_and_b32 s52, s52, 1
	s_xor_b32 s58, s56, 3
	s_cmp_eq_u32 s52, 0
	s_cselect_b32 s52, s56, s58
	s_or_b32 s58, s52, s57
	s_lshl_b32 s56, s62, 8
	s_lshl_b32 s52, s58, 6
	s_and_b32 s59, s56, 0xf800
	s_add_i32 s52, s52, s59
	v_or_b32_e32 v4, s52, v194
	s_lshl_b32 s52, s62, 6
	v_mov_b64_e32 v[0:1], s[50:51]
	s_and_b32 s63, s52, 0x180
	v_mad_u64_u32 v[0:1], s[56:57], v4, s83, v[0:1]
	s_lshl_b32 s52, s63, 1
	s_waitcnt vmcnt(1)
	v_lshl_add_u64 v[18:19], v[0:1], 0, s[52:53]
	v_or_b32_e32 v0, s59, v169
	v_mul_u32_u24_e32 v0, 0x600, v0
	v_lshlrev_b32_e32 v50, 1, v0
	v_mov_b32_e32 v51, v5
	v_lshl_add_u64 v[0:1], s[50:51], 0, v[50:51]
	v_lshl_add_u64 v[0:1], v[0:1], 0, s[52:53]
	v_mov_b32_e32 v173, v5
	s_lshl_b32 s52, s0, 7
	v_lshl_add_u64 v[6:7], v[0:1], 0, v[172:173]
	v_lshl_add_u64 v[0:1], s[52:53], 0, v[158:159]
	s_mov_b32 s0, 0x30000
	v_lshlrev_b64 v[0:1], 12, v[0:1]
	v_add_co_u32_e32 v14, vcc, s0, v6
	v_lshl_add_u64 v[20:21], v[162:163], 0, v[0:1]
	s_nop 0
	v_addc_co_u32_e32 v15, vcc, 0, v7, vcc
	s_mov_b32 s0, 0x20000
	s_waitcnt vmcnt(0)
	v_add_co_u32_e32 v22, vcc, s0, v20
	global_load_dwordx4 v[0:3], v[6:7], off offset:1024
	s_nop 0
	global_load_dwordx4 v[6:9], v[6:7], off offset:1152
	s_nop 0
	global_load_dwordx4 v[10:13], v[14:15], off offset:1024
	global_load_dwordx4 v[26:29], v[20:21], off
	v_addc_co_u32_e32 v23, vcc, 0, v21, vcc
	global_load_dwordx4 v[14:17], v[14:15], off offset:1152
	s_nop 0
	global_load_dwordx4 v[30:33], v[22:23], off
	v_add_co_u32_e32 v22, vcc, s85, v20
	s_mov_b32 s0, 0x60000
	s_nop 0
	v_addc_co_u32_e32 v23, vcc, 0, v21, vcc
	v_add_co_u32_e32 v20, vcc, s0, v20
	v_lshl_add_u64 v[18:19], v[154:155], 1, v[18:19]
	v_mov_b32_e32 v171, v5
	v_addc_co_u32_e32 v21, vcc, 0, v21, vcc
	global_load_dwordx4 v[34:37], v[22:23], off
	global_load_dwordx4 v[38:41], v[20:21], off
	v_lshl_add_u64 v[22:23], v[18:19], 0, v[170:171]
	global_load_dwordx4 v[18:21], v[22:23], off
	s_nop 0
	global_load_dwordx4 v[22:25], v[22:23], off offset:64
	v_mov_b32_e32 v70, v5
	v_mov_b32_e32 v71, v5
	v_mov_b32_e32 v72, v5
	v_mov_b32_e32 v73, v5
	v_mov_b64_e32 v[66:67], v[70:71]
	v_mov_b64_e32 v[62:63], v[70:71]
	v_mov_b64_e32 v[54:55], v[70:71]
	v_mov_b64_e32 v[46:47], v[70:71]
	v_mov_b64_e32 v[42:43], v[70:71]
	s_and_b32 s65, s58, 0x7ffffffe
	v_or3_b32 v176, v168, s1, v50
	v_mov_b64_e32 v[50:51], v[70:71]
	v_mov_b64_e32 v[58:59], v[70:71]
	s_mov_b32 s52, 0
	v_mov_b32_e32 v177, v157
	v_mov_b32_e32 v171, 0
	v_mov_b32_e32 v210, 0xff800000
	v_mov_b64_e32 v[68:69], v[72:73]
	v_mov_b64_e32 v[64:65], v[72:73]
	v_mov_b64_e32 v[56:57], v[72:73]
	v_mov_b64_e32 v[48:49], v[72:73]
	v_mov_b64_e32 v[44:45], v[72:73]
	s_lshr_b32 s59, s58, 1
	s_add_i32 s64, s58, -1
	s_add_i32 s65, s65, 2
	v_mov_b64_e32 v[52:53], v[72:73]
	v_mov_b64_e32 v[60:61], v[72:73]
	s_mov_b32 s70, 0
	s_waitcnt vmcnt(9)
	ds_write_b128 v190, v[0:3]
	s_waitcnt vmcnt(8)
	ds_write_b128 v190, v[6:9] offset:18432
	s_waitcnt vmcnt(7)
	ds_write_b128 v190, v[10:13] offset:9216
	s_waitcnt vmcnt(5)
	ds_write_b128 v190, v[14:17] offset:27648
	ds_write_b128 v192, v[26:29] offset:36864
	s_waitcnt vmcnt(4)
	ds_write_b128 v192, v[30:33] offset:45568
	s_waitcnt vmcnt(3)
	ds_write_b128 v192, v[34:37] offset:54272
	s_waitcnt vmcnt(2)
	ds_write_b128 v192, v[38:41] offset:62976
	s_waitcnt vmcnt(0) lgkmcnt(0)
	s_barrier
	s_branch .LBB0_2651

; __device__ __forceinline__ void phase_attn(KP P, int l_, unsigned char* shm) {
;     ...
;             const unsigned char* base = shm + (t & 1) * STG;
; #pragma unroll
;             for (int hf = 0; hf < 2; ++hf) {
;                 const int kb = 2 * t + hf;
;                 if (kb <= qb) {
;                     const u16* Ks = (const u16*)(base + mp * KT_B) + hf * 64 * KROW;
;                     const u16* Vt = (const u16*)(base + 2 * KT_B) + hf * 64;
.LBB0_2653:
	s_bitcmp1_b32 s70, 0
	s_cselect_b32 s0, 0x11800, 0
	s_add_i32 s0, s0, 0
	v_add_u32_e32 v75, s0, v170
	v_add3_u32 v74, s0, v193, v170
	v_add_u32_e32 v209, v75, v199
	s_cmp_gt_u32 s52, s58
	v_add_u32_e32 v208, v74, v198
	v_add_u32_e32 v207, 0x9000, v209
	v_add_u32_e32 v206, 0xa000, v209
	v_add_u32_e32 v205, 0xb000, v209
	v_add_u32_e32 v204, 0xc000, v209
	v_add_u32_e32 v203, 0xd000, v209
	v_add_u32_e32 v202, 0xe000, v209
	v_add_u32_e32 v173, 0xf000, v209
	s_cbranch_scc0 .LBB0_2656
	s_cmp_ge_u32 s52, s58
	s_cbranch_scc0 .LBB0_2659

; __device__ __forceinline__ void phase_attn(KP P, int l_, unsigned char* shm) {
;     ...
;                 if (kb <= qb) {
;                     const u16* Ks = (const u16*)(base + mp * KT_B) + hf * 64 * KROW;
;                     const u16* Vt = (const u16*)(base + 2 * KT_B) + hf * 64;
;                     f32x4 st[4];
;                     bf16x8 kfr[4][2];
; #pragma unroll
;                     for (int kt = 0; kt < 4; ++kt)
; #pragma unroll
;                         for (int ks = 0; ks < 2; ++ks) kfr[kt][ks] = *(const bf16x8*)(Ks + (kt * 16 + l15) * KROW + ks * 32 + g * 8);
;                     uint2 vfa[8][2], vfb[8][2];
; #pragma unroll
;                     for (int e = 0; e < 8; ++e)
; #pragma unroll
;                         for (int k2 = 0; k2 < 2; ++k2) { const u16* vp = Vt + (e * 16 + l15) * VROW + k2 * 32 + g * 4; vfa[e][k2] = *(const uint2*)vp; vfb[e][k2] = *(const uint2*)(vp + 16); }
;                     __builtin_amdgcn_sched_barrier(0);
; #pragma unroll
;                     for (int kt = 0; kt < 4; ++kt) { st[kt] = (f32x4){0.f, 0.f, 0.f, 0.f};
; #pragma unroll
;                         for (int ks = 0; ks < 2; ++ks) st[kt] = __builtin_amdgcn_mfma_f32_16x16x32_bf16(kfr[kt][ks], qf[ks], st[kt], 0, 0, 0); }
;                     if (kb == qb) {
;                         asm volatile("" ::: "memory");
;                         const int qr = rq * 16 + l15;
; #pragma unroll
;                         for (int kt = 0; kt < 4; ++kt)
; #pragma unroll
;                             for (int jj = 0; jj < 4; ++jj) if (kt * 16 + g * 4 + jj > qr) st[kt][jj] = -INFINITY;
;                     }
.LBB0_2656:
	ds_read_b128 v[138:141], v208
	ds_read_b128 v[142:145], v208 offset:64
	ds_read_b128 v[146:149], v208 offset:2304
	ds_read_b128 v[212:215], v208 offset:2368
	ds_read_b128 v[216:219], v208 offset:4608
	ds_read_b128 v[220:223], v208 offset:4672
	ds_read_b128 v[224:227], v208 offset:6912
	ds_read_b128 v[242:245], v208 offset:6976
	ds_read_b128 v[134:137], v207
	ds_read_b128 v[130:133], v207 offset:64
	ds_read_b128 v[126:129], v206 offset:256
	ds_read_b128 v[122:125], v206 offset:320
	ds_read_b128 v[118:121], v205 offset:512
	ds_read_b128 v[114:117], v205 offset:576
	ds_read_b128 v[110:113], v204 offset:768
	ds_read_b128 v[106:109], v204 offset:832
	ds_read_b128 v[102:105], v203 offset:1024
	ds_read_b128 v[98:101], v203 offset:1088
	ds_read_b128 v[94:97], v202 offset:1280
	ds_read_b128 v[90:93], v202 offset:1344
	ds_read_b128 v[86:89], v173 offset:1536
	ds_read_b128 v[82:85], v173 offset:1600
	v_add_u32_e32 v74, 0x7000, v207
	ds_read_b128 v[78:81], v74 offset:1792
	ds_read_b128 v[74:77], v74 offset:1856
	s_waitcnt lgkmcnt(14)
	v_mfma_f32_16x16x32_bf16 v[138:141], v[138:141], v[18:21], 0
	s_cmp_lg_u32 s58, s52
	v_mfma_f32_16x16x32_bf16 v[150:153], v[142:145], v[22:25], v[138:141]
	v_mfma_f32_16x16x32_bf16 v[138:141], v[146:149], v[18:21], 0
	v_mfma_f32_16x16x32_bf16 v[146:149], v[212:215], v[22:25], v[138:141]
	v_mfma_f32_16x16x32_bf16 v[138:141], v[216:219], v[18:21], 0
	v_mfma_f32_16x16x32_bf16 v[142:145], v[224:227], v[18:21], 0
	v_mfma_f32_16x16x32_bf16 v[138:141], v[220:223], v[22:25], v[138:141]
	v_mfma_f32_16x16x32_bf16 v[142:145], v[242:245], v[22:25], v[142:145]
	s_cbranch_scc1 .LBB0_2658
	s_nop 0
	v_cndmask_b32_e64 v186, v150, v241, s[8:9]
	v_cndmask_b32_e64 v150, v186, v150, s[10:11]
	v_cndmask_b32_e64 v151, v241, v151, s[10:11]
	v_cndmask_b32_e64 v152, v152, v241, s[12:13]
	v_cndmask_b32_e64 v153, v153, v241, s[14:15]
	v_cndmask_b32_e64 v146, v146, v241, s[16:17]
	v_cndmask_b32_e64 v147, v147, v241, s[18:19]
	v_cndmask_b32_e64 v148, v148, v241, s[20:21]
	v_cndmask_b32_e64 v149, v149, v241, s[22:23]
	v_cndmask_b32_e64 v138, v138, v241, s[24:25]
	v_cndmask_b32_e64 v139, v139, v241, s[26:27]
	v_cndmask_b32_e64 v140, v140, v241, s[28:29]
	v_cndmask_b32_e64 v141, v141, v241, s[30:31]
	v_cndmask_b32_e64 v142, v142, v241, s[34:35]
	v_cndmask_b32_e64 v143, v143, v241, s[36:37]
	v_cndmask_b32_e64 v144, v144, v241, s[38:39]
	v_cndmask_b32_e64 v145, v145, v241, s[40:41]

; __device__ __forceinline__ void phase_attn(KP P, int l_, unsigned char* shm) {
;     ...
;                 if (kb <= qb) {
;                     const u16* Ks = (const u16*)(base + mp * KT_B) + hf * 64 * KROW;
;                     const u16* Vt = (const u16*)(base + 2 * KT_B) + hf * 64;
;                     f32x4 st[4];
;                     bf16x8 kfr[4][2];
; #pragma unroll
;                     for (int kt = 0; kt < 4; ++kt)
; #pragma unroll
;                         for (int ks = 0; ks < 2; ++ks) kfr[kt][ks] = *(const bf16x8*)(Ks + (kt * 16 + l15) * KROW + ks * 32 + g * 8);
;                     uint2 vfa[8][2], vfb[8][2];
; #pragma unroll
;                     for (int e = 0; e < 8; ++e)
; #pragma unroll
;                         for (int k2 = 0; k2 < 2; ++k2) { const u16* vp = Vt + (e * 16 + l15) * VROW + k2 * 32 + g * 4; vfa[e][k2] = *(const uint2*)vp; vfb[e][k2] = *(const uint2*)(vp + 16); }
;                     __builtin_amdgcn_sched_barrier(0);
; #pragma unroll
;                     for (int kt = 0; kt < 4; ++kt) { st[kt] = (f32x4){0.f, 0.f, 0.f, 0.f};
; #pragma unroll
;                         for (int ks = 0; ks < 2; ++ks) st[kt] = __builtin_amdgcn_mfma_f32_16x16x32_bf16(kfr[kt][ks], qf[ks], st[kt], 0, 0, 0); }
;                     if (kb == qb) {
;                         asm volatile("" ::: "memory");
;                         const int qr = rq * 16 + l15;
; #pragma unroll
;                         for (int kt = 0; kt < 4; ++kt)
; #pragma unroll
;                             for (int jj = 0; jj < 4; ++jj) if (kt * 16 + g * 4 + jj > qr) st[kt][jj] = -INFINITY;
;                     }
.LBB0_2659:
	ds_read_b128 v[138:141], v208 offset:9216
	ds_read_b128 v[142:145], v208 offset:9280
	ds_read_b128 v[146:149], v208 offset:11520
	ds_read_b128 v[212:215], v208 offset:11584
	ds_read_b128 v[216:219], v208 offset:13824
	ds_read_b128 v[220:223], v208 offset:13888
	ds_read_b128 v[224:227], v208 offset:16128
	ds_read_b128 v[242:245], v208 offset:16192
	ds_read_b128 v[134:137], v207 offset:128
	ds_read_b128 v[130:133], v207 offset:192
	ds_read_b128 v[126:129], v206 offset:384
	ds_read_b128 v[122:125], v206 offset:448
	ds_read_b128 v[118:121], v205 offset:640
	ds_read_b128 v[114:117], v205 offset:704
	ds_read_b128 v[110:113], v204 offset:896
	ds_read_b128 v[106:109], v204 offset:960
	ds_read_b128 v[102:105], v203 offset:1152
	ds_read_b128 v[98:101], v203 offset:1216
	ds_read_b128 v[94:97], v202 offset:1408
	ds_read_b128 v[90:93], v202 offset:1472
	ds_read_b128 v[86:89], v173 offset:1664
	ds_read_b128 v[82:85], v173 offset:1728
	v_add_u32_e32 v74, 0x9080, v209
	v_add_u32_e32 v74, 0x7000, v74
	ds_read_b128 v[78:81], v74 offset:1792
	ds_read_b128 v[74:77], v74 offset:1856
	s_waitcnt lgkmcnt(14)
	v_mfma_f32_16x16x32_bf16 v[138:141], v[138:141], v[18:21], 0
	s_cmp_lg_u32 s64, s52
	v_mfma_f32_16x16x32_bf16 v[150:153], v[142:145], v[22:25], v[138:141]
	v_mfma_f32_16x16x32_bf16 v[138:141], v[146:149], v[18:21], 0
	v_mfma_f32_16x16x32_bf16 v[146:149], v[212:215], v[22:25], v[138:141]
	v_mfma_f32_16x16x32_bf16 v[138:141], v[216:219], v[18:21], 0
	v_mfma_f32_16x16x32_bf16 v[142:145], v[224:227], v[18:21], 0
	v_mfma_f32_16x16x32_bf16 v[138:141], v[220:223], v[22:25], v[138:141]
	v_mfma_f32_16x16x32_bf16 v[142:145], v[242:245], v[22:25], v[142:145]
	s_cbranch_scc1 .LBB0_2661
	s_nop 0
	v_cndmask_b32_e64 v173, v150, v241, s[8:9]
	v_cndmask_b32_e64 v150, v173, v150, s[10:11]
	v_cndmask_b32_e64 v151, v241, v151, s[10:11]
	v_cndmask_b32_e64 v152, v152, v241, s[12:13]
	v_cndmask_b32_e64 v153, v153, v241, s[14:15]
	v_cndmask_b32_e64 v146, v146, v241, s[16:17]
	v_cndmask_b32_e64 v147, v147, v241, s[18:19]
	v_cndmask_b32_e64 v148, v148, v241, s[20:21]
	v_cndmask_b32_e64 v149, v149, v241, s[22:23]
	v_cndmask_b32_e64 v138, v138, v241, s[24:25]
	v_cndmask_b32_e64 v139, v139, v241, s[26:27]
	v_cndmask_b32_e64 v140, v140, v241, s[28:29]
	v_cndmask_b32_e64 v141, v141, v241, s[30:31]
	v_cndmask_b32_e64 v142, v142, v241, s[34:35]
	v_cndmask_b32_e64 v143, v143, v241, s[36:37]
	v_cndmask_b32_e64 v144, v144, v241, s[38:39]
	v_cndmask_b32_e64 v145, v145, v241, s[40:41]
